# stack: + passC Q x state LDS reads batched
# speedup vs baseline: 1.0015x; 1.0015x over previous
; #define LAS __attribute__((address_space(3)))
; DI unsigned f2bf(float f) { unsigned u = __builtin_bit_cast(unsigned, f); return (u + 0x7fffu + ((u >> 16) & 1u)) >> 16; }
; DI f32x4 mfma16(bf16x8 a, bf16x8 b, f32x4 c) { return __builtin_amdgcn_mfma_f32_16x16x32_bf16(a, b, c, 0, 0, 0); }
; DI void hgrn_passC(const Params& P, LAS unsigned char* lds, int u) {
;     ...
;         const u32x4 gv = *(const u32x4*)(U + (size_t)(tok0 + ch * 32 + nc) * LDU_E + 5120 + h * 128 + nv0);
;         __syncthreads();
;         f32x4 ao[2];
; #pragma unroll
;         for (int ci = 0; ci < 2; ++ci) { ao[ci] = (f32x4){0.f, 0.f, 0.f, 0.f};
; #pragma unroll
;             for (int ks = 0; ks < 4; ++ks) { const bf16x8 a = *(const LAS bf16x8*)(Qs + (16 * ci + r16) * 272 + (32 * ks + 8 * g) * 2);
;                 const bf16x8 bs = *(const LAS bf16x8*)(ST + (16 * w + r16) * 272 + (32 * ks + 8 * g) * 2);
;                 ao[ci] = mfma16(a, bs, ao[ci]); } }
;         if (w < 4) { const int ci = w >> 1, si = w & 1; f32x4 s = (f32x4){0.f, 0.f, 0.f, 0.f};
; #pragma unroll
;             for (int ks = 0; ks < 4; ++ks) { const bf16x8 a = *(const LAS bf16x8*)(Qs + (16 * ci + r16) * 272 + (32 * ks + 8 * g) * 2);
;                 const bf16x8 bk = *(const LAS bf16x8*)(Ks + (16 * si + r16) * 272 + (32 * ks + 8 * g) * 2);
;                 s = mfma16(a, bk, s); }
; #pragma unroll
;             for (int j = 0; j < 4; ++j) { const int c = 16 * ci + 4 * g + j, sidx = 16 * si + r16;
;                 *(LAS bf16_t*)(Ps + c * 80 + sidx * 2) = (bf16_t)f2bf(sidx <= c ? s[j] : 0.f); } }
.LBB0_102:
	v_mov_b64_e32 v[56:57], s[20:21]
	v_mad_i64_i32 v[56:57], s[12:13], v72, s86, v[56:57]
	v_lshl_add_u64 v[56:57], v[56:57], 0, s[10:11]
	v_lshl_add_u64 v[56:57], v[56:57], 0, v[0:1]
	v_add_co_u32_e32 v56, vcc, 0x2000, v56
	v_add_u32_e32 v73, v69, v68
	s_nop 0
	v_addc_co_u32_e32 v57, vcc, 0, v57, vcc
	global_load_dwordx4 v[56:59], v[56:57], off offset:2048
	s_waitcnt lgkmcnt(0)
	s_barrier
	ds_read_b128 v[152:155], v73 offset:40448
	ds_read_b128 v[156:159], v73 offset:40512
	ds_read_b128 v[160:163], v73 offset:40576
	ds_read_b128 v[164:167], v73 offset:40640
	ds_read_b128 v[168:171], v87
	ds_read_b128 v[172:175], v87 offset:64
	ds_read_b128 v[176:179], v87 offset:128
	ds_read_b128 v[180:183], v87 offset:192
	ds_read_b128 v[184:187], v87 offset:4352
	ds_read_b128 v[188:191], v87 offset:4416
	ds_read_b128 v[192:195], v87 offset:4480
	ds_read_b128 v[196:199], v87 offset:4544
	s_waitcnt lgkmcnt(0)
	v_mfma_f32_16x16x32_bf16 v[60:63], v[168:171], v[152:155], 0
	v_mfma_f32_16x16x32_bf16 v[64:67], v[184:187], v[152:155], 0
	v_mfma_f32_16x16x32_bf16 v[60:63], v[172:175], v[156:159], v[60:63]
	v_mfma_f32_16x16x32_bf16 v[64:67], v[188:191], v[156:159], v[64:67]
	v_mfma_f32_16x16x32_bf16 v[60:63], v[176:179], v[160:163], v[60:63]
	v_mfma_f32_16x16x32_bf16 v[64:67], v[192:195], v[160:163], v[64:67]
	v_mfma_f32_16x16x32_bf16 v[60:63], v[180:183], v[164:167], v[60:63]
	v_mfma_f32_16x16x32_bf16 v[64:67], v[196:199], v[164:167], v[64:67]
	s_and_saveexec_b64 s[34:35], s[38:39]
	s_cbranch_execz .LBB0_95
	ds_read_b128 v[96:99], v88
	v_add_u32_e32 v73, v84, v68
	ds_read_b128 v[100:103], v73 offset:8704
	s_waitcnt lgkmcnt(0)
	v_mfma_f32_16x16x32_bf16 v[96:99], v[96:99], v[100:103], 0
	ds_read_b128 v[100:103], v88 offset:64
	ds_read_b128 v[104:107], v73 offset:8768
	s_waitcnt lgkmcnt(0)
	v_mfma_f32_16x16x32_bf16 v[96:99], v[100:103], v[104:107], v[96:99]
	ds_read_b128 v[100:103], v88 offset:128
	ds_read_b128 v[104:107], v73 offset:8832
	s_waitcnt lgkmcnt(0)
	v_mfma_f32_16x16x32_bf16 v[96:99], v[100:103], v[104:107], v[96:99]
	ds_read_b128 v[100:103], v88 offset:192
	ds_read_b128 v[104:107], v73 offset:8896
	s_waitcnt lgkmcnt(0)
	v_mfma_f32_16x16x32_bf16 v[96:99], v[100:103], v[104:107], v[96:99]
	s_nop 7
	v_cndmask_b32_e64 v73, v96, 0, s[40:41]
	v_bfe_u32 v74, v73, 16, 1
	v_add3_u32 v73, v73, v74, s92
	ds_write_b16_d16_hi v89, v73 offset:37888
	v_cndmask_b32_e64 v73, v97, 0, s[42:43]
	v_bfe_u32 v74, v73, 16, 1
	v_add3_u32 v73, v73, v74, s92
	ds_write_b16_d16_hi v89, v73 offset:37968
	v_cndmask_b32_e64 v73, v98, 0, s[44:45]
	v_bfe_u32 v74, v73, 16, 1
	v_add3_u32 v73, v73, v74, s92
	ds_write_b16_d16_hi v89, v73 offset:38048
	v_cndmask_b32_e64 v73, v99, 0, s[46:47]
	v_bfe_u32 v74, v73, 16, 1
	v_add3_u32 v73, v73, v74, s92
	ds_write_b16_d16_hi v89, v73 offset:38128
	s_branch .LBB0_95
